# P7 small-tile GEMM: touch-prefetch two K-steps ahead, loop wait vmcnt(8)
# baseline (speedup 1.0000x reference)
; #define SG_LOAD(k0) do { _Pragma("unroll") for (int i_ = 0; i_ < 4; ++i_) { const int id_ = tid + i_ * 512, rr_ = id_ >> 5, cc_ = id_ & 31; \
;         ra[i_] = *(const u32x4*)(Ag + (size_t)rr_ * lda + (k0) + cc_ * 8); rb[i_] = *(const u32x4*)(Bg + (size_t)rr_ * ldb + (k0) + cc_ * 8); } } while (0)
; template <class Epi>
; __device__ __forceinline__ void small_gemm_tile(unsigned char* lds, const bf16_t* A, int lda, const bf16_t* Bt, int ldb, int K, int kbreak, int rowbase, int tm, int tn, const Epi& E, int tid) {
;     ...
;     const bf16_t* Ag = A + (size_t)(rowbase + tm * 64) * lda; const bf16_t* Bg = Bt + (size_t)(tn * 64) * ldb;
;     u32x4 ra[4], rb[4];
;     ...
;     f32x4 cur[2], first[2];
; #pragma unroll
;     for (int n_ = 0; n_ < 2; ++n_) { cur[n_] = (f32x4){0.f, 0.f, 0.f, 0.f}; first[n_] = (f32x4){0.f, 0.f, 0.f, 0.f}; }
;     SG_LOAD(0);
.LBB0_1000:
	s_and_b32 s16, s25, 31
	s_lshl_b32 s16, s16, 20
	v_lshl_add_u64 v[66:67], v[56:57], 0, s[16:17]
	v_lshl_add_u64 v[68:69], v[58:59], 0, s[16:17]
	v_lshl_add_u64 v[70:71], v[60:61], 0, s[16:17]
	s_lshl_b32 s16, s26, 1
	s_andn2_b32 s16, s16, 63
	s_add_i32 s20, s16, 0x4000
	s_and_b32 s27, s26, 31
	s_ashr_i32 s21, s20, 31
	s_lshl_b64 s[22:23], s[20:21], 14
	s_lshl_b32 s16, s27, 20
	v_lshl_add_u64 v[16:17], v[42:43], 0, s[22:23]
	v_lshl_add_u64 v[18:19], v[44:45], 0, s[16:17]
	v_lshl_add_u64 v[8:9], v[16:17], 0, v[46:47]
	v_lshl_add_u64 v[10:11], v[18:19], 0, v[46:47]
	v_lshl_add_u64 v[20:21], v[16:17], 0, v[48:49]
	v_lshl_add_u64 v[22:23], v[18:19], 0, v[48:49]
	v_lshl_add_u64 v[28:29], v[16:17], 0, v[50:51]
	v_lshl_add_u64 v[30:31], v[18:19], 0, v[50:51]
	v_lshl_add_u64 v[16:17], v[16:17], 0, v[52:53]
	global_load_dwordx4 v[0:3], v[8:9], off
	global_load_dwordx4 v[4:7], v[10:11], off
	s_nop 0
	global_load_dwordx4 v[8:11], v[20:21], off
	global_load_dwordx4 v[12:15], v[22:23], off
	s_nop 0
	global_load_dwordx4 v[20:23], v[28:29], off
	global_load_dwordx4 v[24:27], v[30:31], off
	v_lshl_add_u64 v[18:19], v[18:19], 0, v[52:53]
	global_load_dwordx4 v[28:31], v[16:17], off
	global_load_dwordx4 v[32:35], v[18:19], off
	s_and_b32 s22, s3, 0xffffffc0
	s_ashr_i32 s23, s22, 31
	s_lshl_b64 s[22:23], s[22:23], 14
	v_lshl_add_u64 v[72:73], v[62:63], 0, s[22:23]
	v_lshl_add_u64 v[74:75], v[64:65], 0, s[22:23]
	v_lshl_add_u64 v[76:77], v[60:61], 0, s[22:23]
	s_mov_b32 s16, 0
	v_mov_b32_e32 v36, 0
	v_mov_b32_e32 v37, v41
	v_mov_b32_e32 v38, v41
	v_mov_b32_e32 v39, v41
	v_mov_b32_e32 v16, 0
	v_mov_b32_e32 v17, v41
	v_mov_b32_e32 v18, v41
	v_mov_b32_e32 v19, v41
	v_lshl_add_u64 v[250:251], v[76:77], 0, v[54:55]
	v_add_co_u32_e32 v252, vcc, 0x1c600000, v250
	s_nop 1
	v_addc_co_u32_e32 v253, vcc, 0, v251, vcc
	global_load_dword v254, v[252:253], off offset:512
	v_add_co_u32_e32 v252, vcc, 0x1c680000, v250
	s_nop 1
	v_addc_co_u32_e32 v253, vcc, 0, v251, vcc
	global_load_dword v254, v[252:253], off offset:512
	v_lshl_add_u64 v[250:251], v[70:71], 0, v[54:55]
	v_add_co_u32_e32 v252, vcc, 0x6400000, v250
	s_nop 1
	v_addc_co_u32_e32 v253, vcc, 0, v251, vcc
	global_load_dword v254, v[252:253], off offset:512
	v_add_co_u32_e32 v252, vcc, 0x6480000, v250
	s_nop 1
	v_addc_co_u32_e32 v253, vcc, 0, v251, vcc
	global_load_dword v254, v[252:253], off offset:512
	v_lshl_add_u64 v[250:251], v[74:75], 0, v[54:55]
	global_load_dword v254, v[250:251], off offset:0
	v_lshl_add_u64 v[252:253], v[68:69], 0, v[54:55]
	global_load_dword v254, v[252:253], off offset:0
	v_lshl_add_u64 v[250:251], v[72:73], 0, v[54:55]
	global_load_dword v254, v[250:251], off offset:0
	v_lshl_add_u64 v[252:253], v[66:67], 0, v[54:55]
	global_load_dword v254, v[252:253], off offset:0
	v_lshl_add_u64 v[250:251], v[76:77], 0, v[54:55]
	v_add_co_u32_e32 v252, vcc, 0x1c600000, v250
	s_nop 1
	v_addc_co_u32_e32 v253, vcc, 0, v251, vcc
	global_load_dword v254, v[252:253], off offset:1024
	v_add_co_u32_e32 v252, vcc, 0x1c680000, v250
	s_nop 1
	v_addc_co_u32_e32 v253, vcc, 0, v251, vcc
	global_load_dword v254, v[252:253], off offset:1024
	v_lshl_add_u64 v[250:251], v[70:71], 0, v[54:55]
	v_add_co_u32_e32 v252, vcc, 0x6400000, v250
	s_nop 1
	v_addc_co_u32_e32 v253, vcc, 0, v251, vcc
	global_load_dword v254, v[252:253], off offset:1024
	v_add_co_u32_e32 v252, vcc, 0x6480000, v250
	s_nop 1
	v_addc_co_u32_e32 v253, vcc, 0, v251, vcc
	global_load_dword v254, v[252:253], off offset:1024
	v_lshl_add_u64 v[250:251], v[74:75], 0, v[54:55]
	global_load_dword v254, v[250:251], off offset:512
	v_lshl_add_u64 v[252:253], v[68:69], 0, v[54:55]
	global_load_dword v254, v[252:253], off offset:512
	v_lshl_add_u64 v[250:251], v[72:73], 0, v[54:55]
	global_load_dword v254, v[250:251], off offset:512
	v_lshl_add_u64 v[252:253], v[66:67], 0, v[54:55]
	global_load_dword v254, v[252:253], off offset:512
	s_branch .LBB0_1002

; #define LBAR() asm volatile("s_waitcnt lgkmcnt(0)\n\ts_barrier" ::: "memory")
; #define SG_LOAD(k0) do { _Pragma("unroll") for (int i_ = 0; i_ < 4; ++i_) { const int id_ = tid + i_ * 512, rr_ = id_ >> 5, cc_ = id_ & 31; \
;         ra[i_] = *(const u32x4*)(Ag + (size_t)rr_ * lda + (k0) + cc_ * 8); rb[i_] = *(const u32x4*)(Bg + (size_t)rr_ * ldb + (k0) + cc_ * 8); } } while (0)
; template <class Epi>
; __device__ __forceinline__ void small_gemm_tile(unsigned char* lds, const bf16_t* A, int lda, const bf16_t* Bt, int ldb, int K, int kbreak, int rowbase, int tm, int tn, const Epi& E, int tid) {
;     ...
;     for (int k0 = 0; k0 < K; k0 += 256) {
; #pragma unroll
;         for (int i = 0; i < 4; ++i) { const int id = tid + i * 512, rr = id >> 5, cc = id & 31; *(u32x4*)(AS + rr * 528 + cc * 16) = ra[i]; *(u32x4*)(BS + rr * 528 + cc * 16) = rb[i]; }
;         LBAR();
;         if (k0 + 256 < K) SG_LOAD(k0 + 256);
.LBB0_1002:
	s_waitcnt vmcnt(8)
	ds_write_b128 v83, v[0:3]
	ds_write_b128 v83, v[4:7] offset:33792
	ds_write_b128 v84, v[8:11]
	ds_write_b128 v84, v[12:15] offset:33792
	ds_write_b128 v83, v[20:23] offset:16896
	ds_write_b128 v83, v[24:27] offset:50688
	ds_write_b128 v85, v[28:31]
	ds_write_b128 v85, v[32:35] offset:33792
	s_waitcnt lgkmcnt(0)
	s_barrier
	s_cmpk_gt_u32 s16, 0x1eff
	s_cselect_b64 s[22:23], -1, 0
	s_cmpk_lt_u32 s16, 0x1f00
	s_cbranch_scc0 .LBB0_1001
	v_lshl_add_u64 v[20:21], v[76:77], 0, v[54:55]
	v_add_co_u32_e32 v0, vcc, 0x1c600000, v20
	v_lshl_add_u64 v[24:25], v[70:71], 0, v[54:55]
	s_nop 0
	v_addc_co_u32_e32 v1, vcc, 0, v21, vcc
	v_add_co_u32_e32 v4, vcc, 0x6400000, v24
	v_lshl_add_u64 v[8:9], v[74:75], 0, v[54:55]
	s_nop 0
	v_addc_co_u32_e32 v5, vcc, 0, v25, vcc
	v_add_co_u32_e32 v20, vcc, 0x1c680000, v20
	v_lshl_add_u64 v[12:13], v[68:69], 0, v[54:55]
	s_nop 0
	v_addc_co_u32_e32 v21, vcc, 0, v21, vcc
	v_add_co_u32_e32 v24, vcc, 0x6480000, v24
	v_lshl_add_u64 v[28:29], v[72:73], 0, v[54:55]
	s_nop 0
	v_addc_co_u32_e32 v25, vcc, 0, v25, vcc
	v_lshl_add_u64 v[32:33], v[66:67], 0, v[54:55]
	global_load_dwordx4 v[0:3], v[0:1], off offset:512
	s_nop 0
	global_load_dwordx4 v[4:7], v[4:5], off offset:512
	s_nop 0
	global_load_dwordx4 v[8:11], v[8:9], off
	s_nop 0
	global_load_dwordx4 v[12:15], v[12:13], off
	s_nop 0
	global_load_dwordx4 v[20:23], v[20:21], off offset:512
	s_nop 0
	global_load_dwordx4 v[24:27], v[24:25], off offset:512
	s_nop 0
	global_load_dwordx4 v[28:31], v[28:29], off
	s_nop 0
	global_load_dwordx4 v[32:35], v[32:33], off
	v_lshl_add_u64 v[250:251], v[76:77], 0, v[54:55]
	v_add_co_u32_e32 v252, vcc, 0x1c600000, v250
	s_nop 1
	v_addc_co_u32_e32 v253, vcc, 0, v251, vcc
	global_load_dword v254, v[252:253], off offset:1536
	v_add_co_u32_e32 v252, vcc, 0x1c680000, v250
	s_nop 1
	v_addc_co_u32_e32 v253, vcc, 0, v251, vcc
	global_load_dword v254, v[252:253], off offset:1536
	v_lshl_add_u64 v[250:251], v[70:71], 0, v[54:55]
	v_add_co_u32_e32 v252, vcc, 0x6400000, v250
	s_nop 1
	v_addc_co_u32_e32 v253, vcc, 0, v251, vcc
	global_load_dword v254, v[252:253], off offset:1536
	v_add_co_u32_e32 v252, vcc, 0x6480000, v250
	s_nop 1
	v_addc_co_u32_e32 v253, vcc, 0, v251, vcc
	global_load_dword v254, v[252:253], off offset:1536
	v_lshl_add_u64 v[250:251], v[74:75], 0, v[54:55]
	global_load_dword v254, v[250:251], off offset:1024
	v_lshl_add_u64 v[252:253], v[68:69], 0, v[54:55]
	global_load_dword v254, v[252:253], off offset:1024
	v_lshl_add_u64 v[250:251], v[72:73], 0, v[54:55]
	global_load_dword v254, v[250:251], off offset:1024
	v_lshl_add_u64 v[252:253], v[66:67], 0, v[54:55]
	global_load_dword v254, v[252:253], off offset:1024
	s_branch .LBB0_1001

; __global__ void __launch_bounds__(512, 2) hybrid_fwd(Args a) {
;     extern __shared__ __attribute__((aligned(16))) unsigned char lds[];
	.amdhsa_kernel _Z10hybrid_fwd4Args
		.amdhsa_group_segment_fixed_size 0
		.amdhsa_private_segment_fixed_size 0
		.amdhsa_kernarg_size 424
		.amdhsa_user_sgpr_count 2
		.amdhsa_user_sgpr_dispatch_ptr 0
		.amdhsa_user_sgpr_queue_ptr 0
		.amdhsa_user_sgpr_kernarg_segment_ptr 1
		.amdhsa_user_sgpr_dispatch_id 0
		.amdhsa_user_sgpr_kernarg_preload_length 0
		.amdhsa_user_sgpr_kernarg_preload_offset 0
		.amdhsa_user_sgpr_private_segment_size 0
		.amdhsa_uses_dynamic_stack 0
		.amdhsa_enable_private_segment 0
		.amdhsa_system_sgpr_workgroup_id_x 1
		.amdhsa_system_sgpr_workgroup_id_y 0
		.amdhsa_system_sgpr_workgroup_id_z 0
		.amdhsa_system_sgpr_workgroup_info 0
		.amdhsa_system_vgpr_workitem_id 2
		.amdhsa_next_free_vgpr 256
		.amdhsa_next_free_sgpr 98
		.amdhsa_accum_offset 256
		.amdhsa_reserve_vcc 1
		.amdhsa_float_round_mode_32 0
		.amdhsa_float_round_mode_16_64 0
		.amdhsa_float_denorm_mode_32 3
		.amdhsa_float_denorm_mode_16_64 3
		.amdhsa_dx10_clamp 1
		.amdhsa_ieee_mode 1
		.amdhsa_fp16_overflow 0
		.amdhsa_tg_split 0
		.amdhsa_exception_fp_ieee_invalid_op 0
		.amdhsa_exception_fp_denorm_src 0
		.amdhsa_exception_fp_ieee_div_zero 0
		.amdhsa_exception_fp_ieee_overflow 0
		.amdhsa_exception_fp_ieee_underflow 0
		.amdhsa_exception_fp_ieee_inexact 0
		.amdhsa_exception_int_div_zero 0
	.end_amdhsa_kernel

amdhsa.kernels:
  - .agpr_count:     0
    .args:
      - .offset:         0
        .size:           168
        .value_kind:     by_value
      - .offset:         168
        .size:           4
        .value_kind:     hidden_block_count_x
      - .offset:         172
        .size:           4
        .value_kind:     hidden_block_count_y
      - .offset:         176
        .size:           4
        .value_kind:     hidden_block_count_z
      - .offset:         180
        .size:           2
        .value_kind:     hidden_group_size_x
      - .offset:         182
        .size:           2
        .value_kind:     hidden_group_size_y
      - .offset:         184
        .size:           2
        .value_kind:     hidden_group_size_z
      - .offset:         186
        .size:           2
        .value_kind:     hidden_remainder_x
      - .offset:         188
        .size:           2
        .value_kind:     hidden_remainder_y
      - .offset:         190
        .size:           2
        .value_kind:     hidden_remainder_z
      - .offset:         208
        .size:           8
        .value_kind:     hidden_global_offset_x
      - .offset:         216
        .size:           8
        .value_kind:     hidden_global_offset_y
      - .offset:         224
        .size:           8
        .value_kind:     hidden_global_offset_z
      - .offset:         232
        .size:           2
        .value_kind:     hidden_grid_dims
      - .offset:         256
        .size:           8
        .value_kind:     hidden_multigrid_sync_arg
      - .offset:         288
        .size:           4
        .value_kind:     hidden_dynamic_lds_size
    .group_segment_fixed_size: 0
    .kernarg_segment_align: 8
    .kernarg_segment_size: 424
    .language:       OpenCL C
    .language_version:
      - 2
      - 0
    .max_flat_workgroup_size: 512
    .name:           _Z10hybrid_fwd4Args
    .private_segment_fixed_size: 0
    .sgpr_count:     104
    .sgpr_spill_count: 43
    .symbol:         _Z10hybrid_fwd4Args.kd
    .uniform_work_group_size: 1
    .uses_dynamic_stack: false
    .vgpr_count:     256
    .vgpr_spill_count: 0
    .wavefront_size: 64
